# LRU: hoist the 4 c-value ds_read_u16 per tile to tile start (distinct regs), latency off the gate chain
# baseline (speedup 1.0000x reference)
; __device__ __forceinline__ float bf2f(bf16_t b) { return __uint_as_float(((unsigned)b) << 16); }
; __device__ __forceinline__ float sigmoidf(float z) { return __builtin_amdgcn_rcpf(1.0f + __expf(-z)); }
; __device__ void lru_fused_phase(const int bid, const int nblk, bf16_t* __restrict__ U, bf16_t* __restrict__ HF, const bf16_t* __restrict__ Wg, const float* __restrict__ cw, const float* __restrict__ cb, ...
;     ...
;                         const bf16x8 af = *(const bf16x8*)(buf + (16 * rt + fr) * RS + (32 * s + 8 * fq) * 2);
;                         za = __builtin_amdgcn_mfma_f32_16x16x32_bf16(af, Bf[0][s], za, 0, 0, 0);
;                         zi = __builtin_amdgcn_mfma_f32_16x16x32_bf16(af, Bf[1][s], zi, 0, 0, 0);
;                     }
;                     float av[4], bv[4];
; #pragma unroll
;                     for (int j = 0; j < 4; ++j) {
;                         const float c = bf2f(*(const unsigned short*)(buf + (16 * rt + 4 * fq + j) * RS + chl * 2));
;                         const float r = sigmoidf(za[j] + ba), ig = sigmoidf(zi[j] + bi_);
;                         const float la = -sp * r;
;                         av[j] = __expf(la);
;                         bv[j] = __builtin_sqrtf(fmaxf(1.0f - av[j] * av[j], 0.f)) * ig * c;
;                     }
.LBB0_119:
	s_bitcmp1_b32 s2, 0
	s_cselect_b32 s2, 0x4400, 0
	s_add_i32 s2, s2, 0
	v_add_u32_e32 v104, s2, v8
	v_add_u32_e32 v106, v104, v98
	ds_read_b128 v[36:39], v106
	ds_read_b128 v[108:111], v106 offset:64
	v_add_u32_e32 v10, s2, v74
	s_mov_b64 s[2:3], -1
	s_waitcnt lgkmcnt(1)
	v_mfma_f32_16x16x32_bf16 v[40:43], v[36:39], v[0:3], 0
	v_mfma_f32_16x16x32_bf16 v[36:39], v[36:39], v[20:23], 0
	s_waitcnt lgkmcnt(0)
	v_mfma_f32_16x16x32_bf16 v[40:43], v[108:111], v[4:7], v[40:43]
	v_mfma_f32_16x16x32_bf16 v[36:39], v[108:111], v[24:27], v[36:39]
	ds_read_b128 v[108:111], v106 offset:128
	s_waitcnt lgkmcnt(0)
	v_mfma_f32_16x16x32_bf16 v[40:43], v[108:111], v[12:15], v[40:43]
	v_mfma_f32_16x16x32_bf16 v[36:39], v[108:111], v[28:31], v[36:39]
	ds_read_b128 v[108:111], v106 offset:192
	v_add_u32_e32 v106, v10, v99
	s_waitcnt lgkmcnt(0)
	v_mfma_f32_16x16x32_bf16 v[40:43], v[108:111], v[16:19], v[40:43]
	s_nop 7
	ds_read_u16 v153, v106
	ds_read_u16 v154, v106 offset:272
	ds_read_u16 v155, v106 offset:544
	ds_read_u16 v156, v106 offset:816
	v_add_f32_e32 v40, v82, v40
	v_mfma_f32_16x16x32_bf16 v[36:39], v[108:111], v[32:35], v[36:39]
	v_or_b32_e32 v152, s70, v47
	v_xor_b32_e32 v152, 16, v152
	v_mad_u32_u24 v152, v152, s35, v104
	ds_read_b128 v[128:131], v152
	ds_read_b128 v[132:135], v152 offset:64
	ds_read_b128 v[136:139], v152 offset:128
	ds_read_b128 v[140:143], v152 offset:192
	v_mul_f32_e32 v40, 0xbfb8aa3b, v40
	v_exp_f32_e32 v40, v40
	v_add_f32_e32 v41, v82, v41
	v_mul_f32_e32 v41, 0xbfb8aa3b, v41
	v_exp_f32_e32 v41, v41
	s_nop 2
	v_add_f32_e32 v36, v83, v36
	v_mul_f32_e32 v36, 0xbfb8aa3b, v36
	v_add_f32_e32 v40, 1.0, v40
	v_exp_f32_e32 v36, v36
	v_rcp_f32_e32 v40, v40
	v_add_f32_e32 v37, v83, v37
	v_mul_f32_e32 v37, 0xbfb8aa3b, v37
	v_add_f32_e32 v36, 1.0, v36
	v_rcp_f32_e32 v109, v36
	v_mul_f32_e32 v36, v40, v86
	v_mul_f32_e32 v36, 0xbfb8aa3b, v36
	v_exp_f32_e32 v36, v36
	v_add_f32_e32 v41, 1.0, v41
	v_exp_f32_e32 v37, v37
	v_rcp_f32_e32 v41, v41
	v_fma_f32 v40, -v36, v36, 1.0
	v_max_f32_e32 v40, 0, v40
	v_add_f32_e32 v37, 1.0, v37
	v_sqrt_f32_e32 v40, v40
	s_nop 0
	v_add_f32_e32 v42, v82, v42
	v_mul_f32_e32 v42, 0xbfb8aa3b, v42
	v_exp_f32_e32 v42, v42
	v_add_f32_e32 v38, v83, v38
	v_mul_f32_e32 v38, 0xbfb8aa3b, v38
	v_add_f32_e32 v42, 1.0, v42
	v_exp_f32_e32 v38, v38
	v_rcp_f32_e32 v42, v42
	v_mul_f32_e32 v40, v109, v40
	v_rcp_f32_e32 v109, v37
	v_mul_f32_e32 v37, v41, v86
	v_mul_f32_e32 v37, 0xbfb8aa3b, v37
	v_exp_f32_e32 v37, v37
	v_add_f32_e32 v38, 1.0, v38
	v_add_f32_e32 v43, v82, v43
	v_fma_f32 v41, -v37, v37, 1.0
	v_max_f32_e32 v41, 0, v41
	s_waitcnt lgkmcnt(0)
	v_lshlrev_b32_e32 v108, 16, v153
	v_sqrt_f32_e32 v41, v41
	s_nop 0
	v_mul_f32_e32 v40, v40, v108
	v_mul_f32_e32 v43, 0xbfb8aa3b, v43
	v_exp_f32_e32 v43, v43
	s_waitcnt lgkmcnt(0)
	v_lshlrev_b32_e32 v108, 16, v154
	v_add_f32_e32 v39, v83, v39
	s_waitcnt lgkmcnt(0)
	v_mfma_f32_16x16x32_bf16 v[144:147], v[128:131], v[0:3], 0
	v_mfma_f32_16x16x32_bf16 v[148:151], v[128:131], v[20:23], 0
	v_mfma_f32_16x16x32_bf16 v[144:147], v[132:135], v[4:7], v[144:147]
	v_mfma_f32_16x16x32_bf16 v[148:151], v[132:135], v[24:27], v[148:151]
	v_mfma_f32_16x16x32_bf16 v[144:147], v[136:139], v[12:15], v[144:147]
	v_mfma_f32_16x16x32_bf16 v[148:151], v[136:139], v[28:31], v[148:151]
	v_mfma_f32_16x16x32_bf16 v[144:147], v[140:143], v[16:19], v[144:147]
	v_mfma_f32_16x16x32_bf16 v[148:151], v[140:143], v[32:35], v[148:151]
	v_mul_f32_e32 v39, 0xbfb8aa3b, v39
	v_add_f32_e32 v43, 1.0, v43
	v_mul_f32_e32 v41, v109, v41
	v_rcp_f32_e32 v109, v38
	v_mul_f32_e32 v38, v42, v86
	v_mul_f32_e32 v38, 0xbfb8aa3b, v38
	v_exp_f32_e32 v38, v38
	v_mul_f32_e32 v41, v41, v108
	v_exp_f32_e32 v39, v39
	v_fma_f32 v42, -v38, v38, 1.0
	v_max_f32_e32 v42, 0, v42
	v_rcp_f32_e32 v43, v43
	v_sqrt_f32_e32 v42, v42
	s_nop 0
	s_waitcnt lgkmcnt(0)
	v_lshlrev_b32_e32 v108, 16, v155
	v_add_f32_e32 v39, 1.0, v39
	s_waitcnt lgkmcnt(0)
	v_lshlrev_b32_e32 v106, 16, v156
	s_nop 1
	s_nop 1
	v_mul_f32_e32 v42, v109, v42
	v_mul_f32_e32 v42, v42, v108
	v_rcp_f32_e32 v108, v39
	v_mul_f32_e32 v39, v43, v86
	v_mul_f32_e32 v39, 0xbfb8aa3b, v39
	v_exp_f32_e32 v39, v39
	s_nop 0
	v_fma_f32 v43, -v39, v39, 1.0
	v_max_f32_e32 v43, 0, v43
	s_nop 0
	v_sqrt_f32_e32 v43, v43
	s_nop 0
	s_nop 0
	s_nop 0
	s_nop 1
	s_nop 1
	v_mul_f32_e32 v43, v108, v43
	v_mul_f32_e32 v43, v43, v106
	s_and_b64 vcc, exec, s[64:65]
	s_cbranch_vccz .LBB0_121
	v_fma_f32 v108, v38, v43, v42
	v_mul_f32_e32 v109, v38, v39
	v_fma_f32 v111, v37, v108, v41
	v_mul_f32_e32 v110, v37, v109
	v_fma_f32 v112, v36, v111, v40
	v_mul_f32_e32 v106, v36, v110
	s_mov_b64 s[2:3], 0

; __device__ __forceinline__ float bf2f(bf16_t b) { return __uint_as_float(((unsigned)b) << 16); }
; __device__ __forceinline__ float sigmoidf(float z) { return __builtin_amdgcn_rcpf(1.0f + __expf(-z)); }
; __device__ void lru_fused_phase(const int bid, const int nblk, bf16_t* __restrict__ U, bf16_t* __restrict__ HF, const bf16_t* __restrict__ Wg, const float* __restrict__ cw, const float* __restrict__ cb, ...
;     ...
;                         const bf16x8 af = *(const bf16x8*)(buf + (16 * rt + fr) * RS + (32 * s + 8 * fq) * 2);
;                         za = __builtin_amdgcn_mfma_f32_16x16x32_bf16(af, Bf[0][s], za, 0, 0, 0);
;                         zi = __builtin_amdgcn_mfma_f32_16x16x32_bf16(af, Bf[1][s], zi, 0, 0, 0);
;                     }
;                     float av[4], bv[4];
; #pragma unroll
;                     for (int j = 0; j < 4; ++j) {
;                         const float c = bf2f(*(const unsigned short*)(buf + (16 * rt + 4 * fq + j) * RS + chl * 2));
;                         const float r = sigmoidf(za[j] + ba), ig = sigmoidf(zi[j] + bi_);
;                         const float la = -sp * r;
;                         av[j] = __expf(la);
;                         bv[j] = __builtin_sqrtf(fmaxf(1.0f - av[j] * av[j], 0.f)) * ig * c;
;                     }
.LBB0_142:
	s_mov_b64 s[2:3], -1
	s_waitcnt lgkmcnt(1)
	s_waitcnt lgkmcnt(0)
	s_waitcnt lgkmcnt(0)
	v_or_b32_e32 v105, s38, v46
	v_mad_u32_u24 v105, v105, s35, v10
	s_waitcnt lgkmcnt(0)
	v_or_b32_e32 v152, s70, v47
	v_xor_b32_e32 v152, 32, v152
	v_mad_u32_u24 v152, v152, s35, v104
	ds_read_b128 v[128:131], v152
	ds_read_b128 v[132:135], v152 offset:64
	ds_read_b128 v[136:139], v152 offset:128
	ds_read_b128 v[140:143], v152 offset:192
	ds_read_u16 v153, v105
	ds_read_u16 v154, v105 offset:272
	ds_read_u16 v155, v105 offset:544
	ds_read_u16 v156, v105 offset:816
	v_add_f32_e32 v40, v82, v144
	v_mul_f32_e32 v40, 0xbfb8aa3b, v40
	v_exp_f32_e32 v40, v40
	v_add_f32_e32 v41, v82, v145
	v_mul_f32_e32 v41, 0xbfb8aa3b, v41
	v_exp_f32_e32 v41, v41
	s_nop 2
	v_add_f32_e32 v36, v83, v148
	v_mul_f32_e32 v36, 0xbfb8aa3b, v36
	v_add_f32_e32 v40, 1.0, v40
	v_exp_f32_e32 v36, v36
	v_rcp_f32_e32 v40, v40
	v_add_f32_e32 v37, v83, v149
	v_mul_f32_e32 v37, 0xbfb8aa3b, v37
	v_add_f32_e32 v36, 1.0, v36
	v_rcp_f32_e32 v109, v36
	v_mul_f32_e32 v36, v40, v86
	v_mul_f32_e32 v36, 0xbfb8aa3b, v36
	v_exp_f32_e32 v36, v36
	v_add_f32_e32 v41, 1.0, v41
	v_exp_f32_e32 v37, v37
	v_rcp_f32_e32 v41, v41
	v_fma_f32 v40, -v36, v36, 1.0
	v_max_f32_e32 v40, 0, v40
	v_add_f32_e32 v37, 1.0, v37
	v_sqrt_f32_e32 v40, v40
	s_nop 0
	v_add_f32_e32 v42, v82, v146
	v_mul_f32_e32 v42, 0xbfb8aa3b, v42
	v_exp_f32_e32 v42, v42
	v_add_f32_e32 v38, v83, v150
	v_mul_f32_e32 v38, 0xbfb8aa3b, v38
	v_add_f32_e32 v42, 1.0, v42
	v_exp_f32_e32 v38, v38
	v_rcp_f32_e32 v42, v42
	v_mul_f32_e32 v40, v109, v40
	v_rcp_f32_e32 v109, v37
	v_mul_f32_e32 v37, v41, v86
	v_mul_f32_e32 v37, 0xbfb8aa3b, v37
	v_exp_f32_e32 v37, v37
	v_add_f32_e32 v38, 1.0, v38
	v_add_f32_e32 v43, v82, v147
	v_fma_f32 v41, -v37, v37, 1.0
	v_max_f32_e32 v41, 0, v41
	s_waitcnt lgkmcnt(0)
	v_lshlrev_b32_e32 v108, 16, v153
	v_sqrt_f32_e32 v41, v41
	s_nop 0
	v_mul_f32_e32 v40, v40, v108
	v_mul_f32_e32 v43, 0xbfb8aa3b, v43
	v_exp_f32_e32 v43, v43
	s_waitcnt lgkmcnt(0)
	v_lshlrev_b32_e32 v108, 16, v154
	v_add_f32_e32 v39, v83, v151
	s_waitcnt lgkmcnt(0)
	v_mfma_f32_16x16x32_bf16 v[144:147], v[128:131], v[0:3], 0
	v_mfma_f32_16x16x32_bf16 v[148:151], v[128:131], v[20:23], 0
	v_mfma_f32_16x16x32_bf16 v[144:147], v[132:135], v[4:7], v[144:147]
	v_mfma_f32_16x16x32_bf16 v[148:151], v[132:135], v[24:27], v[148:151]
	v_mfma_f32_16x16x32_bf16 v[144:147], v[136:139], v[12:15], v[144:147]
	v_mfma_f32_16x16x32_bf16 v[148:151], v[136:139], v[28:31], v[148:151]
	v_mfma_f32_16x16x32_bf16 v[144:147], v[140:143], v[16:19], v[144:147]
	v_mfma_f32_16x16x32_bf16 v[148:151], v[140:143], v[32:35], v[148:151]
	v_mul_f32_e32 v39, 0xbfb8aa3b, v39
	v_add_f32_e32 v43, 1.0, v43
	v_mul_f32_e32 v41, v109, v41
	v_rcp_f32_e32 v109, v38
	v_mul_f32_e32 v38, v42, v86
	v_mul_f32_e32 v38, 0xbfb8aa3b, v38
	v_exp_f32_e32 v38, v38
	v_mul_f32_e32 v41, v41, v108
	v_exp_f32_e32 v39, v39
	v_fma_f32 v42, -v38, v38, 1.0
	v_max_f32_e32 v42, 0, v42
	v_rcp_f32_e32 v43, v43
	v_sqrt_f32_e32 v42, v42
	s_nop 0
	s_waitcnt lgkmcnt(0)
	v_lshlrev_b32_e32 v108, 16, v155
	v_add_f32_e32 v39, 1.0, v39
	s_waitcnt lgkmcnt(0)
	v_lshlrev_b32_e32 v105, 16, v156
	s_nop 1
	s_nop 1
	v_mul_f32_e32 v42, v109, v42
	v_mul_f32_e32 v42, v42, v108
	v_rcp_f32_e32 v108, v39
	v_mul_f32_e32 v39, v43, v86
	v_mul_f32_e32 v39, 0xbfb8aa3b, v39
	v_exp_f32_e32 v39, v39
	s_nop 0
	v_fma_f32 v43, -v39, v39, 1.0
	v_max_f32_e32 v43, 0, v43
	s_nop 0
	v_sqrt_f32_e32 v43, v43
	s_nop 0
	s_nop 0
	s_nop 0
	s_nop 1
	s_nop 1
	v_mul_f32_e32 v43, v108, v43
	v_mul_f32_e32 v43, v43, v105
	s_and_b64 vcc, exec, s[8:9]
	s_cbranch_vccnz .LBB0_144
	v_fma_f32 v108, v38, v43, v42
	v_mul_f32_e32 v109, v38, v39
	v_fma_f32 v111, v37, v108, v41
	v_mul_f32_e32 v110, v37, v109
	v_fma_f32 v112, v36, v111, v40
	v_mul_f32_e32 v105, v36, v110
	s_mov_b64 s[2:3], 0

; __device__ __forceinline__ float bf2f(bf16_t b) { return __uint_as_float(((unsigned)b) << 16); }
; __device__ __forceinline__ float sigmoidf(float z) { return __builtin_amdgcn_rcpf(1.0f + __expf(-z)); }
; __device__ void lru_fused_phase(const int bid, const int nblk, bf16_t* __restrict__ U, bf16_t* __restrict__ HF, const bf16_t* __restrict__ Wg, const float* __restrict__ cw, const float* __restrict__ cb, ...
;     ...
;                         const bf16x8 af = *(const bf16x8*)(buf + (16 * rt + fr) * RS + (32 * s + 8 * fq) * 2);
;                         za = __builtin_amdgcn_mfma_f32_16x16x32_bf16(af, Bf[0][s], za, 0, 0, 0);
;                         zi = __builtin_amdgcn_mfma_f32_16x16x32_bf16(af, Bf[1][s], zi, 0, 0, 0);
;                     }
;                     float av[4], bv[4];
; #pragma unroll
;                     for (int j = 0; j < 4; ++j) {
;                         const float c = bf2f(*(const unsigned short*)(buf + (16 * rt + 4 * fq + j) * RS + chl * 2));
;                         const float r = sigmoidf(za[j] + ba), ig = sigmoidf(zi[j] + bi_);
;                         const float la = -sp * r;
;                         av[j] = __expf(la);
;                         bv[j] = __builtin_sqrtf(fmaxf(1.0f - av[j] * av[j], 0.f)) * ig * c;
;                     }
.LBB0_165:
	s_mov_b64 s[2:3], -1
	s_waitcnt lgkmcnt(1)
	s_waitcnt lgkmcnt(0)
	s_waitcnt lgkmcnt(0)
	v_or_b32_e32 v106, s38, v46
	v_mad_u32_u24 v106, v106, s35, v10
	s_waitcnt lgkmcnt(0)
	v_or_b32_e32 v152, s70, v47
	v_xor_b32_e32 v152, 48, v152
	v_mad_u32_u24 v152, v152, s35, v104
	ds_read_b128 v[128:131], v152
	ds_read_b128 v[132:135], v152 offset:64
	ds_read_b128 v[136:139], v152 offset:128
	ds_read_b128 v[140:143], v152 offset:192
	ds_read_u16 v153, v106
	ds_read_u16 v154, v106 offset:272
	ds_read_u16 v155, v106 offset:544
	ds_read_u16 v156, v106 offset:816
	v_add_f32_e32 v40, v82, v144
	v_mul_f32_e32 v40, 0xbfb8aa3b, v40
	v_exp_f32_e32 v40, v40
	v_add_f32_e32 v41, v82, v145
	v_mul_f32_e32 v41, 0xbfb8aa3b, v41
	v_exp_f32_e32 v41, v41
	s_nop 2
	v_add_f32_e32 v36, v83, v148
	v_mul_f32_e32 v36, 0xbfb8aa3b, v36
	v_add_f32_e32 v40, 1.0, v40
	v_exp_f32_e32 v36, v36
	v_rcp_f32_e32 v40, v40
	v_add_f32_e32 v37, v83, v149
	v_mul_f32_e32 v37, 0xbfb8aa3b, v37
	v_add_f32_e32 v36, 1.0, v36
	v_rcp_f32_e32 v109, v36
	v_mul_f32_e32 v36, v40, v86
	v_mul_f32_e32 v36, 0xbfb8aa3b, v36
	v_exp_f32_e32 v36, v36
	v_add_f32_e32 v41, 1.0, v41
	v_exp_f32_e32 v37, v37
	v_rcp_f32_e32 v41, v41
	v_fma_f32 v40, -v36, v36, 1.0
	v_max_f32_e32 v40, 0, v40
	v_add_f32_e32 v37, 1.0, v37
	v_sqrt_f32_e32 v40, v40
	s_nop 0
	v_add_f32_e32 v42, v82, v146
	v_mul_f32_e32 v42, 0xbfb8aa3b, v42
	v_exp_f32_e32 v42, v42
	v_add_f32_e32 v38, v83, v150
	v_mul_f32_e32 v38, 0xbfb8aa3b, v38
	v_add_f32_e32 v42, 1.0, v42
	v_exp_f32_e32 v38, v38
	v_rcp_f32_e32 v42, v42
	v_mul_f32_e32 v40, v109, v40
	v_rcp_f32_e32 v109, v37
	v_mul_f32_e32 v37, v41, v86
	v_mul_f32_e32 v37, 0xbfb8aa3b, v37
	v_exp_f32_e32 v37, v37
	v_add_f32_e32 v38, 1.0, v38
	v_add_f32_e32 v43, v82, v147
	v_fma_f32 v41, -v37, v37, 1.0
	v_max_f32_e32 v41, 0, v41
	s_waitcnt lgkmcnt(0)
	v_lshlrev_b32_e32 v108, 16, v153
	v_sqrt_f32_e32 v41, v41
	s_nop 0
	v_mul_f32_e32 v40, v40, v108
	v_mul_f32_e32 v43, 0xbfb8aa3b, v43
	v_exp_f32_e32 v43, v43
	s_waitcnt lgkmcnt(0)
	v_lshlrev_b32_e32 v108, 16, v154
	v_add_f32_e32 v39, v83, v151
	s_waitcnt lgkmcnt(0)
	v_mfma_f32_16x16x32_bf16 v[144:147], v[128:131], v[0:3], 0
	v_mfma_f32_16x16x32_bf16 v[148:151], v[128:131], v[20:23], 0
	v_mfma_f32_16x16x32_bf16 v[144:147], v[132:135], v[4:7], v[144:147]
	v_mfma_f32_16x16x32_bf16 v[148:151], v[132:135], v[24:27], v[148:151]
	v_mfma_f32_16x16x32_bf16 v[144:147], v[136:139], v[12:15], v[144:147]
	v_mfma_f32_16x16x32_bf16 v[148:151], v[136:139], v[28:31], v[148:151]
	v_mfma_f32_16x16x32_bf16 v[144:147], v[140:143], v[16:19], v[144:147]
	v_mfma_f32_16x16x32_bf16 v[148:151], v[140:143], v[32:35], v[148:151]
	v_mul_f32_e32 v39, 0xbfb8aa3b, v39
	v_add_f32_e32 v43, 1.0, v43
	v_mul_f32_e32 v41, v109, v41
	v_rcp_f32_e32 v109, v38
	v_mul_f32_e32 v38, v42, v86
	v_mul_f32_e32 v38, 0xbfb8aa3b, v38
	v_exp_f32_e32 v38, v38
	v_mul_f32_e32 v41, v41, v108
	v_exp_f32_e32 v39, v39
	v_fma_f32 v42, -v38, v38, 1.0
	v_max_f32_e32 v42, 0, v42
	v_rcp_f32_e32 v43, v43
	v_sqrt_f32_e32 v42, v42
	s_nop 0
	s_waitcnt lgkmcnt(0)
	v_lshlrev_b32_e32 v108, 16, v155
	v_add_f32_e32 v39, 1.0, v39
	s_waitcnt lgkmcnt(0)
	v_lshlrev_b32_e32 v106, 16, v156
	s_nop 1
	s_nop 1
	v_mul_f32_e32 v42, v109, v42
	v_mul_f32_e32 v42, v42, v108
	v_rcp_f32_e32 v108, v39
	v_mul_f32_e32 v39, v43, v86
	v_mul_f32_e32 v39, 0xbfb8aa3b, v39
	v_exp_f32_e32 v39, v39
	s_nop 0
	v_fma_f32 v43, -v39, v39, 1.0
	v_max_f32_e32 v43, 0, v43
	s_nop 0
	v_sqrt_f32_e32 v43, v43
	s_nop 0
	s_nop 0
	s_nop 0
	s_nop 1
	s_nop 1
	v_mul_f32_e32 v43, v108, v43
	v_mul_f32_e32 v43, v43, v106
	s_and_b64 vcc, exec, s[8:9]
	s_cbranch_vccnz .LBB0_167
	v_fma_f32 v108, v38, v43, v42
	v_mul_f32_e32 v109, v38, v39
	v_fma_f32 v111, v37, v108, v41
	v_mul_f32_e32 v110, v37, v109
	v_fma_f32 v112, v36, v111, v40
	v_mul_f32_e32 v106, v36, v110
	s_mov_b64 s[2:3], 0

; __device__ __forceinline__ float bf2f(bf16_t b) { return __uint_as_float(((unsigned)b) << 16); }
; __device__ __forceinline__ float sigmoidf(float z) { return __builtin_amdgcn_rcpf(1.0f + __expf(-z)); }
; __device__ void lru_fused_phase(const int bid, const int nblk, bf16_t* __restrict__ U, bf16_t* __restrict__ HF, const bf16_t* __restrict__ Wg, const float* __restrict__ cw, const float* __restrict__ cb, ...
;     ...
;                         const bf16x8 af = *(const bf16x8*)(buf + (16 * rt + fr) * RS + (32 * s + 8 * fq) * 2);
;                         za = __builtin_amdgcn_mfma_f32_16x16x32_bf16(af, Bf[0][s], za, 0, 0, 0);
;                         zi = __builtin_amdgcn_mfma_f32_16x16x32_bf16(af, Bf[1][s], zi, 0, 0, 0);
;                     }
;                     float av[4], bv[4];
; #pragma unroll
;                     for (int j = 0; j < 4; ++j) {
;                         const float c = bf2f(*(const unsigned short*)(buf + (16 * rt + 4 * fq + j) * RS + chl * 2));
;                         const float r = sigmoidf(za[j] + ba), ig = sigmoidf(zi[j] + bi_);
;                         const float la = -sp * r;
;                         av[j] = __expf(la);
;                         bv[j] = __builtin_sqrtf(fmaxf(1.0f - av[j] * av[j], 0.f)) * ig * c;
;                     }
.LBB0_188:
	s_mov_b64 s[2:3], -1
	s_waitcnt lgkmcnt(1)
	s_waitcnt lgkmcnt(0)
	s_waitcnt lgkmcnt(0)
	v_or_b32_e32 v104, s38, v46
	v_mad_u32_u24 v104, v104, s35, v10
	ds_read_u16 v10, v104
	s_waitcnt lgkmcnt(1)
	s_waitcnt lgkmcnt(0)
	v_lshlrev_b32_e32 v105, 16, v10
	s_nop 5
	ds_read_u16 v154, v104 offset:272
	ds_read_u16 v155, v104 offset:544
	ds_read_u16 v156, v104 offset:816
	v_add_f32_e32 v10, v82, v144
	v_mul_f32_e32 v10, 0xbfb8aa3b, v10
	v_exp_f32_e32 v10, v10
	v_add_f32_e32 v41, v82, v145
	v_mul_f32_e32 v41, 0xbfb8aa3b, v41
	v_add_f32_e32 v10, 1.0, v10
	v_rcp_f32_e32 v10, v10
	v_exp_f32_e32 v41, v41
	s_nop 2
	v_add_f32_e32 v36, v83, v148
	v_mul_f32_e32 v36, 0xbfb8aa3b, v36
	v_mul_f32_e32 v10, v10, v86
	v_mul_f32_e32 v10, 0xbfb8aa3b, v10
	v_exp_f32_e32 v10, v10
	v_exp_f32_e32 v36, v36
	v_add_f32_e32 v37, v83, v149
	v_mul_f32_e32 v37, 0xbfb8aa3b, v37
	v_fma_f32 v40, -v10, v10, 1.0
	v_max_f32_e32 v40, 0, v40
	v_add_f32_e32 v36, 1.0, v36
	v_sqrt_f32_e32 v40, v40
	s_nop 0
	v_rcp_f32_e32 v36, v36
	v_add_f32_e32 v41, 1.0, v41
	v_exp_f32_e32 v37, v37
	v_rcp_f32_e32 v41, v41
	v_add_f32_e32 v37, 1.0, v37
	v_add_f32_e32 v42, v82, v146
	v_mul_f32_e32 v42, 0xbfb8aa3b, v42
	v_exp_f32_e32 v42, v42
	v_mul_f32_e32 v36, v36, v40
	v_mul_f32_e32 v36, v36, v105
	v_rcp_f32_e32 v105, v37
	v_mul_f32_e32 v37, v41, v86
	v_mul_f32_e32 v37, 0xbfb8aa3b, v37
	v_exp_f32_e32 v37, v37
	v_add_f32_e32 v38, v83, v150
	v_mul_f32_e32 v38, 0xbfb8aa3b, v38
	v_add_f32_e32 v42, 1.0, v42
	v_fma_f32 v41, -v37, v37, 1.0
	v_max_f32_e32 v41, 0, v41
	v_exp_f32_e32 v38, v38
	v_sqrt_f32_e32 v41, v41
	s_nop 0
	v_rcp_f32_e32 v42, v42
	v_add_f32_e32 v38, 1.0, v38
	v_add_f32_e32 v43, v82, v147
	v_mul_f32_e32 v43, 0xbfb8aa3b, v43
	v_exp_f32_e32 v43, v43
	s_waitcnt lgkmcnt(0)
	v_lshlrev_b32_e32 v40, 16, v154
	v_add_f32_e32 v39, v83, v151
	v_mul_f32_e32 v41, v105, v41
	v_rcp_f32_e32 v105, v38
	v_mul_f32_e32 v38, v42, v86
	v_mul_f32_e32 v38, 0xbfb8aa3b, v38
	v_exp_f32_e32 v38, v38
	v_mul_f32_e32 v40, v41, v40
	v_mul_f32_e32 v39, 0xbfb8aa3b, v39
	v_fma_f32 v42, -v38, v38, 1.0
	v_max_f32_e32 v42, 0, v42
	v_add_f32_e32 v43, 1.0, v43
	v_sqrt_f32_e32 v42, v42
	s_nop 0
	v_exp_f32_e32 v39, v39
	v_rcp_f32_e32 v43, v43
	s_waitcnt lgkmcnt(0)
	v_lshlrev_b32_e32 v41, 16, v155
	v_add_f32_e32 v39, 1.0, v39
	s_nop 1
	s_nop 1
	v_mul_f32_e32 v42, v105, v42
	v_mul_f32_e32 v41, v42, v41
	v_rcp_f32_e32 v104, v39
	v_mul_f32_e32 v39, v43, v86
	v_mul_f32_e32 v39, 0xbfb8aa3b, v39
	v_exp_f32_e32 v39, v39
	s_waitcnt lgkmcnt(0)
	v_lshlrev_b32_e32 v42, 16, v156
	v_fma_f32 v43, -v39, v39, 1.0
	v_max_f32_e32 v43, 0, v43
	s_nop 0
	v_sqrt_f32_e32 v43, v43
	s_nop 0
	s_nop 0
	s_nop 0
	s_nop 1
	s_nop 1
	v_mul_f32_e32 v43, v104, v43
	v_mul_f32_e32 v42, v43, v42
	s_and_b64 vcc, exec, s[8:9]
	s_cbranch_vccnz .LBB0_190
	v_fma_f32 v43, v38, v42, v41
	v_mul_f32_e32 v104, v38, v39
	v_fma_f32 v108, v37, v43, v40
	v_mul_f32_e32 v107, v37, v104
	v_fma_f32 v109, v10, v108, v36
	v_mul_f32_e32 v105, v10, v107
	s_mov_b64 s[2:3], 0
